# attention step A: next-load address scalar work moved behind the closing barrier of the MFMA segment
# baseline (speedup 1.0000x reference)
.LBB0_1053:
	s_setprio 0
	s_waitcnt lgkmcnt(0)
	s_barrier
	s_add_i32 s0, s59, 4
	s_cmp_lt_u32 s59, s48
	s_cselect_b32 s0, s0, s50
	s_lshl_b32 s8, s0, 6
	s_mul_i32 s0, s8, 0x600
	s_mov_b32 s1, 0
	v_lshl_add_u64 v[82:83], s[0:1], 0, v[186:187]
	v_lshl_add_u64 v[84:85], s[0:1], 0, v[188:189]
	global_load_dwordx4 v[86:89], v[82:83], off
	global_load_dwordx4 v[90:93], v[84:85], off
	v_lshl_add_u64 v[82:83], s[8:9], 1, v[142:143]
	global_load_dwordx4 v[82:85], v[82:83], off
	v_add_u32_e32 v248, s60, v160
	ds_read_b128 v[164:167], v248 offset:13312
	ds_read_b128 v[168:171], v248 offset:17920
	ds_read_b128 v[172:175], v248 offset:13344
	ds_read_b128 v[176:179], v248 offset:17952
	ds_read_b128 v[180:183], v248 offset:13376
	ds_read_b128 v[220:223], v248 offset:17984
	ds_read_b128 v[224:227], v248 offset:13408
	ds_read_b128 v[232:235], v248 offset:18016
	s_add_i32 s62, s62, 1
	s_cmp_lt_i32 s62, 0
	s_cselect_b64 s[0:1], -1, 0
	s_add_i32 s4, s61, 64
	s_cmp_le_i32 s4, s51
	s_cselect_b64 s[4:5], -1, 0
	s_or_b64 s[0:1], s[0:1], s[4:5]
	s_not_b64 s[4:5], s[0:1]
	s_andn2_b64 vcc, exec, s[0:1]
	s_cbranch_vccnz .LBB0_1059
	s_cmp_lt_i32 s62, 0
	s_cbranch_scc0 .Lmla_b_mask

.LBB0_1088:
	s_setprio 0
	s_waitcnt lgkmcnt(0)
	s_barrier
	s_add_i32 s0, s54, 4
	s_cmp_lt_u32 s54, s43
	s_cselect_b32 s0, s0, s45
	s_lshl_b32 s8, s0, 6
	v_add_u32_e32 v14, s8, v174
	v_ashrrev_i32_e32 v15, 31, v14
	v_lshlrev_b64 v[14:15], 10, v[14:15]
	v_lshl_add_u64 v[132:133], s[8:9], 1, v[176:177]
	v_lshl_add_u64 v[14:15], v[182:183], 0, v[14:15]
	v_lshl_add_u64 v[128:129], v[132:133], 0, v[178:179]
	global_load_dwordx4 v[136:139], v[14:15], off
	s_nop 0
	global_load_dwordx4 v[128:131], v[128:129], off
	v_lshl_add_u64 v[14:15], v[132:133], 0, v[180:181]
	global_load_dwordx4 v[132:135], v[14:15], off
	v_add_u32_e32 v248, s55, v190
	ds_read_b128 v[196:199], v248 offset:9216
	ds_read_b128 v[200:203], v248 offset:13824
	ds_read_b128 v[204:207], v248 offset:18432
	ds_read_b128 v[208:211], v248 offset:23040
	ds_read_b128 v[212:215], v248 offset:9248
	ds_read_b128 v[216:219], v248 offset:13856
	ds_read_b128 v[220:223], v248 offset:18464
	ds_read_b128 v[224:227], v248 offset:23072
	s_add_i32 s57, s57, 1
	s_cmp_lt_i32 s57, 0
	s_cselect_b64 s[0:1], -1, 0
	s_add_i32 s4, s56, 64
	s_cmp_le_i32 s4, s46
	s_cselect_b64 s[4:5], -1, 0
	s_or_b64 s[0:1], s[0:1], s[4:5]
	s_not_b64 s[4:5], s[0:1]
	s_andn2_b64 vcc, exec, s[0:1]
	s_cbranch_vccnz .LBB0_1094
	s_cmp_lt_i32 s57, 0
	s_cbranch_scc0 .Ldiff_b_mask
